# v24 + delta-rule scan step: 21 packed f32 mul/fma split into scalar pairs (strategy 7.5 packed vs scalar fp32 beside MFMAs), bit-identical
# baseline (speedup 1.0000x reference)
; DI void scan_load(ScanLd& L, const bf16_t* Q2, const float* SCB, const bf16_t* TB, const bf16_t* ATB, int ch, int h, int sl, int wave, int lane) {
;     const int fr = lane & 15, g = lane >> 4, r0 = ch * 64, uidx = ch * 8 + h;
;     const bf16_t* rowp = Q2 + (size_t)(r0 + 16 * wave + fr) * 3072 + h * 128 + 8 * g;
; #pragma unroll
;     for (int s = 0; s < 4; ++s) { L.aQ[s] = *(const uint4*)(rowp + 32 * s); L.aK[s] = *(const uint4*)(rowp + 1024 + 32 * s); }
; #pragma unroll
;     for (int s = 0; s < 2; ++s) { L.aT[s] = *(const uint4*)(TB + (size_t)uidx * 4096 + (16 * wave + fr) * 64 + 32 * s + 8 * g);
;                                   L.aA[s] = *(const uint4*)(ATB + (size_t)uidx * 4096 + (16 * wave + fr) * 64 + 32 * s + 8 * g); }
; #pragma unroll
;     for (int e = 0; e < 4; ++e) L.vv[e] = (unsigned)Q2[(size_t)(r0 + 16 * wave + 4 * g + e) * 3072 + 2048 + h * 128 + sl * 16 + fr];
;     const float* sc = SCB + (size_t)uidx * 256 + 16 * wave + 4 * g;
;     L.scK = *(const float4*)(sc); L.scQ = *(const float4*)(sc + 64); L.kt = *(const float4*)(sc + 128); L.be = *(const float4*)(sc + 192);
;     L.gt = SCB[(size_t)uidx * 256 + 64 + 63];
; }
; DI void scan_step(const ScanLd& cur, f32x4 (&S)[2], bf16_t* OB, bf16_t* sST, bf16_t* sUT, bf16_t* sVT, bf16_t* sV2, bf16_t* kT, int r0, int h, int sl, int wave, int lane) {
;     const int fr = lane & 15, g = lane >> 4;
; #pragma unroll
;     for (int m = 0; m < 2; ++m) { uint2 w; w.x = pack2(S[m][0], S[m][1]); w.y = pack2(S[m][2], S[m][3]); *(uint2*)(sST + fr * 136 + 16 * (2 * wave + m) + 4 * g) = w; }
;     asm volatile("s_waitcnt lgkmcnt(0)" ::: "memory"); __builtin_amdgcn_s_barrier(); asm volatile("" ::: "memory");
;     f32x4 ks = (f32x4){0.f, 0.f, 0.f, 0.f}, oo = (f32x4){0.f, 0.f, 0.f, 0.f};
; #pragma unroll
;     for (int s = 0; s < 4; ++s) {
;         const bf16x8 bS = *(const bf16x8*)(sST + fr * 136 + 32 * s + 8 * g);
;         ks = MFMA16(asbf(cur.aK[s]), bS, ks);
;         oo = MFMA16(asbf(cur.aQ[s]), bS, oo);
;     }
; #pragma unroll
;     for (int s = 0; s < 4; ++s) {
;         const uint4 kv = cur.aK[s]; const unsigned w4[4] = {kv.x, kv.y, kv.z, kv.w};
; #pragma unroll
;         for (int e = 0; e < 4; ++e) { kT[(32 * s + 8 * g + 2 * e) * 72 + 16 * wave + fr] = (bf16_t)(w4[e] & 0xffffu); kT[(32 * s + 8 * g + 2 * e + 1) * 72 + 16 * wave + fr] = (bf16_t)(w4[e] >> 16); }
;     }
.LBB0_368:
	s_add_i32 s23, s23, 1
	s_min_i32 s23, s23, s38
	v_lshl_add_u32 v56, s23, 6, v140
	v_or_b32_e32 v8, v56, v136
	s_lshl_b32 s46, s23, 3
	v_mad_i64_i32 v[12:13], s[30:31], v8, s33, v[180:181]
	s_or_b32 s30, s46, s41
	s_ashr_i32 s31, s30, 31
	s_lshl_b64 s[46:47], s[30:31], 13
	v_or_b32_e32 v64, v56, v138
	v_mov_b64_e32 v[56:57], s[76:77]
	global_load_dwordx4 v[40:43], v[12:13], off
	global_load_dwordx4 v[32:35], v[12:13], off offset:64
	global_load_dwordx4 v[52:55], v[12:13], off offset:2048
	global_load_dwordx4 v[44:47], v[12:13], off offset:2112
	global_load_dwordx4 v[28:31], v[12:13], off offset:128
	global_load_dwordx4 v[8:11], v[12:13], off offset:192
	global_load_dwordx4 v[48:51], v[12:13], off offset:2176
	global_load_dwordx4 v[36:39], v[12:13], off offset:2240
	v_lshl_add_u64 v[12:13], v[144:145], 0, s[46:47]
	v_lshl_add_u64 v[16:17], v[146:147], 0, s[46:47]
	v_mad_i64_i32 v[58:59], s[46:47], v64, s33, v[56:57]
	s_mov_b32 s23, s51
	v_lshl_add_u64 v[58:59], v[58:59], 0, s[22:23]
	v_or_b32_e32 v60, 1, v64
	v_lshl_add_u64 v[58:59], v[58:59], 0, v[212:213]
	v_mad_i64_i32 v[60:61], s[46:47], v60, s33, v[56:57]
	v_lshl_add_u64 v[58:59], v[58:59], 0, s[50:51]
	v_lshl_add_u64 v[60:61], v[60:61], 0, s[22:23]
	v_or_b32_e32 v62, 2, v64
	v_add_co_u32_e32 v58, vcc, s75, v58
	v_lshl_add_u64 v[60:61], v[60:61], 0, v[212:213]
	v_mad_i64_i32 v[62:63], s[46:47], v62, s33, v[56:57]
	v_addc_co_u32_e32 v59, vcc, 0, v59, vcc
	v_lshl_add_u64 v[60:61], v[60:61], 0, s[50:51]
	v_lshl_add_u64 v[62:63], v[62:63], 0, s[22:23]
	v_or_b32_e32 v64, 3, v64
	v_add_co_u32_e32 v60, vcc, s75, v60
	v_lshl_add_u64 v[62:63], v[62:63], 0, v[212:213]
	v_mad_i64_i32 v[56:57], s[46:47], v64, s33, v[56:57]
	v_addc_co_u32_e32 v61, vcc, 0, v61, vcc
	v_lshl_add_u64 v[62:63], v[62:63], 0, s[50:51]
	v_lshl_add_u64 v[56:57], v[56:57], 0, s[22:23]
	v_add_co_u32_e32 v62, vcc, s75, v62
	v_lshl_add_u64 v[56:57], v[56:57], 0, v[212:213]
	s_nop 0
	v_addc_co_u32_e32 v63, vcc, 0, v63, vcc
	v_lshl_add_u64 v[56:57], v[56:57], 0, s[50:51]
	s_lshl_b64 s[30:31], s[30:31], 10
	v_add_co_u32_e32 v56, vcc, s75, v56
	s_add_u32 s30, s78, s30
	s_nop 0
	v_addc_co_u32_e32 v57, vcc, 0, v57, vcc
	s_addc_u32 s31, s79, s31
	global_load_dwordx4 v[20:23], v[12:13], off
	global_load_dwordx4 v[24:27], v[12:13], off offset:64
	s_nop 0
	global_load_dwordx4 v[12:15], v[16:17], off
	s_nop 0
	global_load_dwordx4 v[16:19], v[16:17], off offset:64
	s_nop 0
	global_load_ushort v185, v[58:59], off
	global_load_ushort v208, v[60:61], off
	global_load_ushort v209, v[62:63], off
	global_load_ushort v210, v[56:57], off
	v_lshl_add_u64 v[56:57], v[140:141], 2, s[30:31]
	v_mov_b32_e32 v177, v213
	v_lshl_add_u64 v[68:69], v[56:57], 0, v[176:177]
	global_load_dwordx4 v[64:67], v[68:69], off
	global_load_dwordx4 v[56:59], v[68:69], off offset:256
	global_load_dwordx4 v[60:63], v[68:69], off offset:512
	s_nop 0
	global_load_dwordx4 v[68:71], v[68:69], off offset:768
	s_nop 0
	global_load_dword v186, v213, s[30:31] offset:508
	v_cvt_pk_bf16_f32 v156, v0, v1
	v_cvt_pk_bf16_f32 v157, v2, v3
	v_cvt_pk_bf16_f32 v158, v4, v5
	v_cvt_pk_bf16_f32 v159, v6, v7
	ds_write2_b64 v198, v[156:157], v[158:159] offset1:4
	s_waitcnt lgkmcnt(0)
	s_barrier
	ds_read_b128 v[156:159], v199
	ds_read_b128 v[160:163], v199 offset:64
	ds_read_b128 v[200:203], v199 offset:128
	ds_read_b128 v[204:207], v199 offset:192
	s_waitcnt vmcnt(43)
	ds_write_b16 v187, v120 offset:29696
	ds_write_b16_d16_hi v187, v120 offset:29840
	ds_write_b16 v187, v121 offset:29984
	ds_write_b16_d16_hi v189, v121 offset:29984
	ds_write_b16 v187, v122 offset:30272
	ds_write_b16_d16_hi v189, v122 offset:30272
	ds_write_b16 v187, v123 offset:30560
	ds_write_b16_d16_hi v189, v123 offset:30560
	s_waitcnt vmcnt(42)
	ds_write_b16 v187, v116 offset:34304
	ds_write_b16_d16_hi v189, v116 offset:34304
	ds_write_b16 v187, v117 offset:34592
	ds_write_b16_d16_hi v189, v117 offset:34592
	ds_write_b16 v187, v118 offset:34880
	ds_write_b16_d16_hi v189, v118 offset:34880
	s_waitcnt lgkmcnt(14)
	v_mfma_f32_16x16x32_bf16 v[120:123], v[120:123], v[156:159], 0
	ds_write_b16 v187, v119 offset:35168
	ds_write_b16_d16_hi v189, v119 offset:35168
	s_waitcnt vmcnt(39)
	ds_write_b16 v187, v108 offset:38912
	ds_write_b16_d16_hi v189, v108 offset:38912
	ds_write_b16 v187, v109 offset:39200
	ds_write_b16_d16_hi v189, v109 offset:39200
	ds_write_b16 v187, v110 offset:39488
	ds_write_b16_d16_hi v189, v110 offset:39488
	ds_write_b16 v187, v111 offset:39776
	v_mfma_f32_16x16x32_bf16 v[116:119], v[116:119], v[160:163], v[120:123]
	ds_write_b16_d16_hi v189, v111 offset:39776
	s_waitcnt vmcnt(38)
	ds_write_b16 v187, v96 offset:43520
	ds_write_b16_d16_hi v189, v96 offset:43520
	ds_write_b16 v187, v97 offset:43808
	ds_write_b16_d16_hi v189, v97 offset:43808
	ds_write_b16 v187, v98 offset:44096
	ds_write_b16_d16_hi v189, v98 offset:44096
	ds_write_b16 v187, v99 offset:44384
	ds_write_b16_d16_hi v189, v99 offset:44384
	v_mfma_f32_16x16x32_bf16 v[112:115], v[112:115], v[156:159], 0
	s_waitcnt vmcnt(25)
	v_mul_f32_e32 v2, v188, v2
	v_mul_f32_e32 v3, v188, v3
	v_mul_f32_e32 v0, v188, v0
	v_mul_f32_e32 v1, v188, v1
	v_mul_f32_e32 v6, v188, v6
	v_mul_f32_e32 v7, v188, v7
	v_mfma_f32_16x16x32_bf16 v[108:111], v[108:111], v[200:203], v[116:119]
	v_mul_f32_e64 v4, v188, v4
	v_mul_f32_e64 v5, v188, v5
	s_mov_b32 s23, 0x5040100
	s_add_i32 s30, s45, 1
	v_mfma_f32_16x16x32_bf16 v[104:107], v[104:107], v[160:163], v[112:115]
	s_waitcnt vmcnt(7)
	v_perm_b32 v185, v208, v185, s23
	v_mfma_f32_16x16x32_bf16 v[96:99], v[96:99], v[204:207], v[108:111]
	s_waitcnt vmcnt(5)
	v_perm_b32 v177, v210, v209, s23
	s_add_i32 s23, s45, 2
	s_cmp_ge_u32 s30, s43
	v_mfma_f32_16x16x32_bf16 v[92:95], v[92:95], v[200:203], v[104:107]
	s_cselect_b64 s[30:31], -1, 0
	s_nop 1
	v_mul_f32_e32 v96, v128, v96
	v_mul_f32_e32 v97, v129, v97
	v_mul_f32_e32 v98, v130, v98
	v_mul_f32_e32 v99, v131, v99
	v_lshlrev_b32_e32 v105, 16, v196
	v_lshlrev_b32_e32 v104, 16, v195
	v_fma_f32 v96, v132, v104, -v96
	v_fma_f32 v97, v133, v105, -v97
	v_lshlrev_b32_e32 v105, 16, v194
	v_lshlrev_b32_e32 v104, 16, v175
	v_fma_f32 v98, v134, v104, -v98
	v_fma_f32 v99, v135, v105, -v99
	v_cvt_pk_bf16_f32 v96, v96, v97
	v_cvt_pk_bf16_f32 v97, v98, v99
	ds_write_b64 v191, v[96:97] offset:4352
	s_waitcnt lgkmcnt(0)
	s_barrier
; DI void scan_load(ScanLd& L, const bf16_t* Q2, const float* SCB, const bf16_t* TB, const bf16_t* ATB, int ch, int h, int sl, int wave, int lane) {
;     const int fr = lane & 15, g = lane >> 4, r0 = ch * 64, uidx = ch * 8 + h;
;     const bf16_t* rowp = Q2 + (size_t)(r0 + 16 * wave + fr) * 3072 + h * 128 + 8 * g;
; #pragma unroll
;     for (int s = 0; s < 4; ++s) { L.aQ[s] = *(const uint4*)(rowp + 32 * s); L.aK[s] = *(const uint4*)(rowp + 1024 + 32 * s); }
; #pragma unroll
;     for (int s = 0; s < 2; ++s) { L.aT[s] = *(const uint4*)(TB + (size_t)uidx * 4096 + (16 * wave + fr) * 64 + 32 * s + 8 * g);
;                                   L.aA[s] = *(const uint4*)(ATB + (size_t)uidx * 4096 + (16 * wave + fr) * 64 + 32 * s + 8 * g); }
; #pragma unroll
;     for (int e = 0; e < 4; ++e) L.vv[e] = (unsigned)Q2[(size_t)(r0 + 16 * wave + 4 * g + e) * 3072 + 2048 + h * 128 + sl * 16 + fr];
;     const float* sc = SCB + (size_t)uidx * 256 + 16 * wave + 4 * g;
; DI void scan_step(const ScanLd& cur, f32x4 (&S)[2], bf16_t* OB, bf16_t* sST, bf16_t* sUT, bf16_t* sVT, bf16_t* sV2, bf16_t* kT, int r0, int h, int sl, int wave, int lane) {
;     ...
;     f32x4 vn = (f32x4){0.f, 0.f, 0.f, 0.f};
; #pragma unroll
;     for (int s = 0; s < 2; ++s) vn = MFMA16(asbf(cur.aT[s]), *(const bf16x8*)(sUT + fr * 72 + 32 * s + 8 * g), vn);
;     { uint2 w; w.x = pack2(vn[0], vn[1]); w.y = pack2(vn[2], vn[3]); *(uint2*)(sVT + fr * 72 + 16 * wave + 4 * g) = w;
;       uint2 w2; w2.x = pack2(vn[0] * cur.kt.x, vn[1] * cur.kt.y); w2.y = pack2(vn[2] * cur.kt.z, vn[3] * cur.kt.w); *(uint2*)(sV2 + fr * 72 + 16 * wave + 4 * g) = w2; }
;     asm volatile("s_waitcnt lgkmcnt(0)" ::: "memory"); __builtin_amdgcn_s_barrier(); asm volatile("" ::: "memory");
; #pragma unroll
;     for (int s = 0; s < 2; ++s) oo = MFMA16(asbf(cur.aA[s]), *(const bf16x8*)(sVT + fr * 72 + 32 * s + 8 * g), oo);
; #pragma unroll
;     for (int e = 0; e < 4; ++e) OB[(size_t)(r0 + 16 * wave + 4 * g + e) * 1024 + h * 128 + sl * 16 + fr] = f2bf(oo[e]);
;     bf16x8 b2[2];
; #pragma unroll
;     for (int s = 0; s < 2; ++s) b2[s] = *(const bf16x8*)(sV2 + fr * 72 + 32 * s + 8 * g);
; #pragma unroll
;     for (int m = 0; m < 2; ++m) {
;         S[m] *= cur.gt;
; #pragma unroll
;         for (int s = 0; s < 2; ++s) S[m] = MFMA16(*(const bf16x8*)(kT + (16 * (2 * wave + m) + fr) * 72 + 32 * s + 8 * g), b2[s], S[m]);
;     }
	ds_read_b128 v[96:99], v197 offset:4352
	ds_read_b128 v[104:107], v197 offset:4416
	s_waitcnt lgkmcnt(1)
	v_mfma_f32_16x16x32_bf16 v[84:87], v[84:87], v[96:99], 0
	s_mov_b32 s45, s23
	s_waitcnt lgkmcnt(0)
	v_mfma_f32_16x16x32_bf16 v[84:87], v[88:91], v[104:107], v[84:87]
	v_mfma_f32_16x16x32_bf16 v[72:75], v[72:75], v[204:207], v[92:95]
	s_nop 6
	v_cvt_pk_bf16_f32 v88, v84, v85
	v_cvt_pk_bf16_f32 v89, v86, v87
	v_mul_f32_e32 v84, v124, v84
	v_mul_f32_e32 v85, v125, v85
	v_mul_f32_e32 v86, v126, v86
	v_mul_f32_e32 v87, v127, v87
	v_cvt_pk_bf16_f32 v84, v84, v85
	v_cvt_pk_bf16_f32 v85, v86, v87
	ds_write_b64 v191, v[88:89] offset:6656
	ds_write_b64 v191, v[84:85] offset:8960
	s_waitcnt lgkmcnt(0)
	s_barrier
	ds_read_b128 v[84:87], v197 offset:6656
	ds_read_b128 v[88:91], v197 offset:6720
	v_mul_f32_e32 v74, v102, v74
	v_mul_f32_e32 v75, v103, v75
	v_mul_f32_e32 v72, v100, v72
	v_mul_f32_e32 v73, v101, v73
	s_waitcnt lgkmcnt(1)
	s_nop 0
	v_mfma_f32_16x16x32_bf16 v[72:75], v[80:83], v[84:87], v[72:75]
	s_waitcnt lgkmcnt(0)
	v_mfma_f32_16x16x32_bf16 v[72:75], v[76:79], v[88:91], v[72:75]
	v_add_u32_e32 v76, 64, v184
	v_ashrrev_i32_e32 v77, 31, v76
	v_lshlrev_b64 v[76:77], 11, v[76:77]
	v_lshl_add_u64 v[76:77], v[182:183], 0, v[76:77]
	s_nop 3
	v_cvt_pk_bf16_f32 v72, v72, s0
	global_store_short v[76:77], v72, off
	v_add_u32_e32 v72, 0x41, v184
	v_cvt_pk_bf16_f32 v76, v73, s0
	v_ashrrev_i32_e32 v73, 31, v72
	v_lshlrev_b64 v[72:73], 11, v[72:73]
	v_lshl_add_u64 v[72:73], v[182:183], 0, v[72:73]
	global_store_short v[72:73], v76, off
	v_add_u32_e32 v72, 0x42, v184
	ds_read_b128 v[76:79], v192 offset:29696
	v_ashrrev_i32_e32 v73, 31, v72
	v_lshlrev_b64 v[72:73], 11, v[72:73]
	v_cvt_pk_bf16_f32 v74, v74, s0
	v_lshl_add_u64 v[72:73], v[182:183], 0, v[72:73]
	global_store_short v[72:73], v74, off
	ds_read_b128 v[80:83], v192 offset:29760
	ds_read_b128 v[84:87], v197 offset:8960
	ds_read_b128 v[88:91], v197 offset:9024
	ds_read_b128 v[92:95], v192 offset:32000
	s_waitcnt lgkmcnt(2)
	v_mfma_f32_16x16x32_bf16 v[0:3], v[76:79], v[84:87], v[0:3]
	v_cvt_pk_bf16_f32 v78, v75, s0
	ds_read_b128 v[72:75], v192 offset:32064
	v_add_u32_e32 v76, 0x43, v184
	s_waitcnt lgkmcnt(1)
	v_mfma_f32_16x16x32_bf16 v[4:7], v[92:95], v[84:87], v[4:7]
	v_ashrrev_i32_e32 v77, 31, v76
	v_lshlrev_b64 v[76:77], 11, v[76:77]
	v_lshl_add_u64 v[76:77], v[182:183], 0, v[76:77]
	v_mfma_f32_16x16x32_bf16 v[0:3], v[80:83], v[88:91], v[0:3]
	v_add_u32_e32 v184, 0x80, v184
	global_store_short v[76:77], v78, off
	s_waitcnt lgkmcnt(0)
	v_mfma_f32_16x16x32_bf16 v[4:7], v[72:75], v[88:91], v[4:7]
	s_andn2_b64 vcc, exec, s[30:31]
	s_cbranch_vccz .LBB0_341
.LBB0_369:
	s_add_i32 s23, s42, s45
	s_min_i32 s30, s23, s38
	s_waitcnt vmcnt(8)
	v_lshl_add_u32 v100, s30, 6, v140
	v_or_b32_e32 v72, v100, v136
	s_lshl_b32 s46, s30, 3
	v_mad_i64_i32 v[76:77], s[30:31], v72, s33, v[180:181]
	s_or_b32 s30, s46, s41
	s_ashr_i32 s31, s30, 31
	s_lshl_b64 s[46:47], s[30:31], 13
	s_waitcnt vmcnt(7)
	v_or_b32_e32 v128, v100, v138
	v_mov_b64_e32 v[100:101], s[76:77]
	global_load_dwordx4 v[112:115], v[76:77], off
	global_load_dwordx4 v[104:107], v[76:77], off offset:64
	global_load_dwordx4 v[120:123], v[76:77], off offset:2048
	global_load_dwordx4 v[116:119], v[76:77], off offset:2112
	global_load_dwordx4 v[92:95], v[76:77], off offset:128
	global_load_dwordx4 v[72:75], v[76:77], off offset:192
	global_load_dwordx4 v[108:111], v[76:77], off offset:2176
	global_load_dwordx4 v[96:99], v[76:77], off offset:2240
	v_lshl_add_u64 v[76:77], v[144:145], 0, s[46:47]
	v_lshl_add_u64 v[78:79], v[146:147], 0, s[46:47]
	v_mad_i64_i32 v[102:103], s[46:47], v128, s33, v[100:101]
	v_lshl_add_u64 v[102:103], v[102:103], 0, s[26:27]
	s_waitcnt vmcnt(14)
	v_or_b32_e32 v124, 1, v128
	v_lshl_add_u64 v[102:103], v[102:103], 0, v[212:213]
	s_lshl_b32 s50, s39, 1
	v_mad_i64_i32 v[124:125], s[46:47], v124, s33, v[100:101]
	v_lshl_add_u64 v[102:103], v[102:103], 0, s[50:51]
	v_lshl_add_u64 v[124:125], v[124:125], 0, s[26:27]
	v_or_b32_e32 v126, 2, v128
	v_add_co_u32_e32 v102, vcc, s75, v102
	v_lshl_add_u64 v[124:125], v[124:125], 0, v[212:213]
	v_mad_i64_i32 v[126:127], s[46:47], v126, s33, v[100:101]
	v_addc_co_u32_e32 v103, vcc, 0, v103, vcc
	v_lshl_add_u64 v[124:125], v[124:125], 0, s[50:51]
	v_lshl_add_u64 v[126:127], v[126:127], 0, s[26:27]
	v_or_b32_e32 v128, 3, v128
	v_add_co_u32_e32 v124, vcc, s75, v124
	v_lshl_add_u64 v[126:127], v[126:127], 0, v[212:213]
	v_mad_i64_i32 v[100:101], s[46:47], v128, s33, v[100:101]
	v_addc_co_u32_e32 v125, vcc, 0, v125, vcc
	v_lshl_add_u64 v[126:127], v[126:127], 0, s[50:51]
	v_lshl_add_u64 v[100:101], v[100:101], 0, s[26:27]
	v_add_co_u32_e32 v126, vcc, s75, v126
	v_lshl_add_u64 v[100:101], v[100:101], 0, v[212:213]
	s_nop 0
	v_addc_co_u32_e32 v127, vcc, 0, v127, vcc
	v_lshl_add_u64 v[100:101], v[100:101], 0, s[50:51]
	s_lshl_b64 s[30:31], s[30:31], 10
	v_add_co_u32_e32 v100, vcc, s75, v100
	s_add_u32 s30, s78, s30
	s_nop 0
	v_addc_co_u32_e32 v101, vcc, 0, v101, vcc
	s_addc_u32 s31, s79, s31
	global_load_dwordx4 v[84:87], v[76:77], off
	global_load_dwordx4 v[88:91], v[76:77], off offset:64
	global_load_dwordx4 v[80:83], v[78:79], off
	s_nop 0
	global_load_dwordx4 v[76:79], v[78:79], off offset:64
	s_nop 0
	global_load_ushort v195, v[102:103], off
	global_load_ushort v196, v[124:125], off
	global_load_ushort v175, v[126:127], off
	global_load_ushort v194, v[100:101], off
	v_lshl_add_u64 v[100:101], v[140:141], 2, s[30:31]
	s_waitcnt vmcnt(21)
	v_lshl_add_u64 v[132:133], v[100:101], 0, v[178:179]
	global_load_dwordx4 v[100:103], v[132:133], off offset:256
	global_load_dwordx4 v[128:131], v[132:133], off
	global_load_dwordx4 v[124:127], v[132:133], off offset:512
	s_nop 0
	global_load_dwordx4 v[132:135], v[132:133], off offset:768
	s_nop 0
	global_load_dword v188, v213, s[30:31] offset:508
	v_cvt_pk_bf16_f32 v156, v0, v1
	v_cvt_pk_bf16_f32 v157, v2, v3
	v_add_u32_e32 v198, v139, v142
	v_cvt_pk_bf16_f32 v158, v4, v5
	v_cvt_pk_bf16_f32 v159, v6, v7
	ds_write2_b64 v198, v[156:157], v[158:159] offset1:4
	s_waitcnt lgkmcnt(0)
	s_barrier
; DI void scan_step(const ScanLd& cur, f32x4 (&S)[2], bf16_t* OB, bf16_t* sST, bf16_t* sUT, bf16_t* sVT, bf16_t* sV2, bf16_t* kT, int r0, int h, int sl, int wave, int lane) {
;     ...
;     asm volatile("s_waitcnt lgkmcnt(0)" ::: "memory"); __builtin_amdgcn_s_barrier(); asm volatile("" ::: "memory");
;     f32x4 ks = (f32x4){0.f, 0.f, 0.f, 0.f}, oo = (f32x4){0.f, 0.f, 0.f, 0.f};
; #pragma unroll
;     for (int s = 0; s < 4; ++s) {
;         const bf16x8 bS = *(const bf16x8*)(sST + fr * 136 + 32 * s + 8 * g);
;         ks = MFMA16(asbf(cur.aK[s]), bS, ks);
;         oo = MFMA16(asbf(cur.aQ[s]), bS, oo);
;     }
; #pragma unroll
;     for (int s = 0; s < 4; ++s) {
;         const uint4 kv = cur.aK[s]; const unsigned w4[4] = {kv.x, kv.y, kv.z, kv.w};
; #pragma unroll
;         for (int e = 0; e < 4; ++e) { kT[(32 * s + 8 * g + 2 * e) * 72 + 16 * wave + fr] = (bf16_t)(w4[e] & 0xffffu); kT[(32 * s + 8 * g + 2 * e + 1) * 72 + 16 * wave + fr] = (bf16_t)(w4[e] >> 16); }
;     }
;     { uint2 w; w.x = pack2(lo16(cur.vv[0]) * cur.be.x - cur.scK.x * ks[0], lo16(cur.vv[1]) * cur.be.y - cur.scK.y * ks[1]);
;       w.y = pack2(lo16(cur.vv[2]) * cur.be.z - cur.scK.z * ks[2], lo16(cur.vv[3]) * cur.be.w - cur.scK.w * ks[3]);
;       *(uint2*)(sUT + fr * 72 + 16 * wave + 4 * g) = w; }
;     oo[0] *= cur.scQ.x; oo[1] *= cur.scQ.y; oo[2] *= cur.scQ.z; oo[3] *= cur.scQ.w;
;     asm volatile("s_waitcnt lgkmcnt(0)" ::: "memory"); __builtin_amdgcn_s_barrier(); asm volatile("" ::: "memory");
;     f32x4 vn = (f32x4){0.f, 0.f, 0.f, 0.f};
; #pragma unroll
;     for (int s = 0; s < 2; ++s) vn = MFMA16(asbf(cur.aT[s]), *(const bf16x8*)(sUT + fr * 72 + 32 * s + 8 * g), vn);
;     { uint2 w; w.x = pack2(vn[0], vn[1]); w.y = pack2(vn[2], vn[3]); *(uint2*)(sVT + fr * 72 + 16 * wave + 4 * g) = w;
;       uint2 w2; w2.x = pack2(vn[0] * cur.kt.x, vn[1] * cur.kt.y); w2.y = pack2(vn[2] * cur.kt.z, vn[3] * cur.kt.w); *(uint2*)(sV2 + fr * 72 + 16 * wave + 4 * g) = w2; }
;     asm volatile("s_waitcnt lgkmcnt(0)" ::: "memory"); __builtin_amdgcn_s_barrier(); asm volatile("" ::: "memory");
; #pragma unroll
;     for (int s = 0; s < 2; ++s) oo = MFMA16(asbf(cur.aA[s]), *(const bf16x8*)(sVT + fr * 72 + 32 * s + 8 * g), oo);
; #pragma unroll
;     for (int e = 0; e < 4; ++e) OB[(size_t)(r0 + 16 * wave + 4 * g + e) * 1024 + h * 128 + sl * 16 + fr] = f2bf(oo[e]);
;     bf16x8 b2[2];
; #pragma unroll
	v_add_u32_e32 v199, v137, v143
	ds_read_b128 v[156:159], v199
	ds_read_b128 v[160:163], v199 offset:64
	ds_read_b128 v[200:203], v199 offset:128
	ds_read_b128 v[204:207], v199 offset:192
	ds_write_b16 v187, v52 offset:11264
	ds_write_b16_d16_hi v187, v52 offset:11408
	ds_write_b16 v187, v53 offset:11552
	ds_write_b16_d16_hi v189, v53 offset:11552
	ds_write_b16 v187, v54 offset:11840
	ds_write_b16_d16_hi v189, v54 offset:11840
	ds_write_b16 v187, v55 offset:12128
	ds_write_b16_d16_hi v189, v55 offset:12128
	ds_write_b16 v187, v44 offset:15872
	ds_write_b16_d16_hi v189, v44 offset:15872
	ds_write_b16 v187, v45 offset:16160
	ds_write_b16_d16_hi v189, v45 offset:16160
	ds_write_b16 v187, v46 offset:16448
	ds_write_b16_d16_hi v189, v46 offset:16448
	s_waitcnt lgkmcnt(14)
	v_mfma_f32_16x16x32_bf16 v[52:55], v[52:55], v[156:159], 0
	ds_write_b16 v187, v47 offset:16736
	ds_write_b16_d16_hi v189, v47 offset:16736
	ds_write_b16 v187, v48 offset:20480
	ds_write_b16_d16_hi v189, v48 offset:20480
	ds_write_b16 v187, v49 offset:20768
	ds_write_b16_d16_hi v189, v49 offset:20768
	ds_write_b16 v187, v50 offset:21056
	ds_write_b16_d16_hi v189, v50 offset:21056
	ds_write_b16 v187, v51 offset:21344
	v_mfma_f32_16x16x32_bf16 v[40:43], v[40:43], v[156:159], 0
	ds_write_b16_d16_hi v189, v51 offset:21344
	ds_write_b16 v187, v36 offset:25088
	ds_write_b16_d16_hi v189, v36 offset:25088
	ds_write_b16 v187, v37 offset:25376
	ds_write_b16_d16_hi v189, v37 offset:25376
	ds_write_b16 v187, v38 offset:25664
	ds_write_b16_d16_hi v189, v38 offset:25664
	ds_write_b16 v187, v39 offset:25952
	ds_write_b16_d16_hi v189, v39 offset:25952
	v_mfma_f32_16x16x32_bf16 v[44:47], v[44:47], v[160:163], v[52:55]
	v_add_u32_e32 v197, v190, v143
	s_waitcnt vmcnt(21)
	v_mul_f32_e32 v2, v186, v2
	v_mul_f32_e32 v3, v186, v3
	v_mul_f32_e32 v0, v186, v0
	v_mul_f32_e32 v1, v186, v1
	v_mfma_f32_16x16x32_bf16 v[32:35], v[32:35], v[160:163], v[40:43]
	v_mul_f32_e64 v6, v6, v186
	v_mul_f32_e64 v7, v7, v186
	v_mul_f32_e32 v4, v4, v186
	v_mul_f32_e32 v5, v5, v186
	s_cmp_ge_u32 s45, s43
	v_mfma_f32_16x16x32_bf16 v[40:43], v[48:51], v[200:203], v[44:47]
	v_mfma_f32_16x16x32_bf16 v[28:31], v[28:31], v[200:203], v[32:35]
	v_mfma_f32_16x16x32_bf16 v[32:35], v[36:39], v[204:207], v[40:43]
	v_and_b32_e32 v37, 0xffff0000, v185
	v_lshlrev_b32_e32 v36, 16, v185
	v_ashrrev_i32_e32 v185, 31, v184
	v_mfma_f32_16x16x32_bf16 v[8:11], v[8:11], v[204:207], v[28:31]
	s_nop 2
	v_add_u32_e32 v28, 3, v184
	v_mul_f32_e32 v32, v64, v32
	v_mul_f32_e32 v33, v65, v33
	v_mul_f32_e32 v34, v66, v34
	v_mul_f32_e32 v35, v67, v35
	v_fma_f32 v32, v68, v36, -v32
	v_fma_f32 v33, v69, v37, -v33
	v_and_b32_e32 v37, 0xffff0000, v177
	v_lshlrev_b32_e32 v36, 16, v177
	v_fma_f32 v34, v70, v36, -v34
	v_fma_f32 v35, v71, v37, -v35
	v_cvt_pk_bf16_f32 v32, v32, v33
	v_cvt_pk_bf16_f32 v33, v34, v35
	ds_write_b64 v191, v[32:33] offset:4352
	s_waitcnt lgkmcnt(0)
	s_barrier
	ds_read_b128 v[32:35], v197 offset:4352
	ds_read_b128 v[36:39], v197 offset:4416
	s_waitcnt lgkmcnt(1)
	v_mfma_f32_16x16x32_bf16 v[20:23], v[20:23], v[32:35], 0
	v_mul_f32_e64 v10, v58, v10
	v_mul_f32_e64 v11, v59, v11
	v_mul_f32_e32 v8, v56, v8
	v_mul_f32_e32 v9, v57, v9
	v_ashrrev_i32_e32 v29, 31, v28
	s_waitcnt lgkmcnt(0)
	v_mfma_f32_16x16x32_bf16 v[20:23], v[24:27], v[36:39], v[20:23]
	s_nop 7
	v_cvt_pk_bf16_f32 v24, v20, v21
	v_cvt_pk_bf16_f32 v25, v22, v23
	v_mul_f32_e32 v20, v60, v20
	v_mul_f32_e32 v21, v61, v21
	v_mul_f32_e32 v22, v62, v22
	v_mul_f32_e32 v23, v63, v23
	v_cvt_pk_bf16_f32 v20, v20, v21
	v_cvt_pk_bf16_f32 v21, v22, v23
	ds_write_b64 v191, v[24:25] offset:6656
	ds_write_b64 v191, v[20:21] offset:8960
	s_waitcnt lgkmcnt(0)
	s_barrier
	ds_read_b128 v[20:23], v197 offset:6656
	ds_read_b128 v[24:27], v197 offset:6720
	s_waitcnt lgkmcnt(1)
	v_mfma_f32_16x16x32_bf16 v[8:11], v[12:15], v[20:23], v[8:11]
	v_lshlrev_b64 v[12:13], 11, v[184:185]
	v_lshl_add_u64 v[12:13], v[182:183], 0, v[12:13]
	s_waitcnt lgkmcnt(0)
	v_mfma_f32_16x16x32_bf16 v[8:11], v[16:19], v[24:27], v[8:11]
	s_nop 7
	v_cvt_pk_bf16_f32 v8, v8, s0
	global_store_short v[12:13], v8, off
	v_add_u32_e32 v8, 1, v184
	v_cvt_pk_bf16_f32 v12, v9, s0
	v_ashrrev_i32_e32 v9, 31, v8
	v_lshlrev_b64 v[8:9], 11, v[8:9]
	v_lshl_add_u64 v[8:9], v[182:183], 0, v[8:9]
	global_store_short v[8:9], v12, off
	v_add_u32_e32 v8, 2, v184
	ds_read_b128 v[12:15], v192 offset:11264
	v_ashrrev_i32_e32 v9, 31, v8
	v_lshlrev_b64 v[8:9], 11, v[8:9]
	v_cvt_pk_bf16_f32 v10, v10, s0
	v_lshl_add_u64 v[8:9], v[182:183], 0, v[8:9]
	global_store_short v[8:9], v10, off
	v_cvt_pk_bf16_f32 v30, v11, s0
	ds_read_b128 v[8:11], v192 offset:11328
	ds_read_b128 v[16:19], v197 offset:8960
	ds_read_b128 v[20:23], v197 offset:9024
	ds_read_b128 v[24:27], v192 offset:13568
	s_waitcnt lgkmcnt(2)
	v_mfma_f32_16x16x32_bf16 v[0:3], v[12:15], v[16:19], v[0:3]
	ds_read_b128 v[12:15], v192 offset:13632
	s_waitcnt lgkmcnt(1)
	v_mfma_f32_16x16x32_bf16 v[4:7], v[24:27], v[16:19], v[4:7]
	v_mfma_f32_16x16x32_bf16 v[0:3], v[8:11], v[20:23], v[0:3]
	v_lshlrev_b64 v[8:9], 11, v[28:29]
	v_lshl_add_u64 v[8:9], v[182:183], 0, v[8:9]
	global_store_short v[8:9], v30, off
	s_waitcnt lgkmcnt(0)
	v_mfma_f32_16x16x32_bf16 v[4:7], v[12:15], v[20:23], v[4:7]
	s_cbranch_scc0 .LBB0_368
	s_branch .LBB0_341
